# prologue adaLN GEMV: 32 weight rows per wait instead of 4
# speedup vs baseline: 1.0074x; 1.0050x over previous
; DEV void phase_prologue(const Params& p, char* smem) {
;     ...
;       const int cc = tid & 63, kg = tid >> 6;
;       float a[5] = {0, 0, 0, 0, 0};
;       const float* wp = p.w_ada + (size_t)l * 1024 * 3072 + n0 + cc;
; #pragma unroll 4
;       for (int k = kg * 128; k < kg * 128 + 128; ++k) {
;         const float w = wp[(size_t)k * 3072];
; #pragma unroll
;         for (int rr = 0; rr < 5; ++rr) a[rr] += sv[rr * 1024 + k] * w;
;       }
.LBB0_515:
	v_lshl_add_u64 v[12:13], v[2:3], 0, s[8:9]
	global_load_dword v60, v[12:13], off
	v_add_co_u32_e32 v12, vcc, s79, v12
	s_nop 1
	v_addc_co_u32_e32 v13, vcc, 0, v13, vcc
	global_load_dword v62, v[12:13], off
	v_add_co_u32_e32 v12, vcc, s79, v12
	s_nop 1
	v_addc_co_u32_e32 v13, vcc, 0, v13, vcc
	global_load_dword v64, v[12:13], off
	v_add_co_u32_e32 v12, vcc, s79, v12
	s_nop 1
	v_addc_co_u32_e32 v13, vcc, 0, v13, vcc
	global_load_dword v66, v[12:13], off
	v_add_co_u32_e32 v12, vcc, s79, v12
	s_nop 1
	v_addc_co_u32_e32 v13, vcc, 0, v13, vcc
	global_load_dword v68, v[12:13], off
	v_add_co_u32_e32 v12, vcc, s79, v12
	s_nop 1
	v_addc_co_u32_e32 v13, vcc, 0, v13, vcc
	global_load_dword v70, v[12:13], off
	v_add_co_u32_e32 v12, vcc, s79, v12
	s_nop 1
	v_addc_co_u32_e32 v13, vcc, 0, v13, vcc
	global_load_dword v72, v[12:13], off
	v_add_co_u32_e32 v12, vcc, s79, v12
	s_nop 1
	v_addc_co_u32_e32 v13, vcc, 0, v13, vcc
	global_load_dword v74, v[12:13], off
	v_add_co_u32_e32 v12, vcc, s79, v12
	s_nop 1
	v_addc_co_u32_e32 v13, vcc, 0, v13, vcc
	global_load_dword v76, v[12:13], off
	v_add_co_u32_e32 v12, vcc, s79, v12
	s_nop 1
	v_addc_co_u32_e32 v13, vcc, 0, v13, vcc
	global_load_dword v78, v[12:13], off
	v_add_co_u32_e32 v12, vcc, s79, v12
	s_nop 1
	v_addc_co_u32_e32 v13, vcc, 0, v13, vcc
	global_load_dword v80, v[12:13], off
	v_add_co_u32_e32 v12, vcc, s79, v12
	s_nop 1
	v_addc_co_u32_e32 v13, vcc, 0, v13, vcc
	global_load_dword v82, v[12:13], off
	v_add_co_u32_e32 v12, vcc, s79, v12
	s_nop 1
	v_addc_co_u32_e32 v13, vcc, 0, v13, vcc
	global_load_dword v84, v[12:13], off
	v_add_co_u32_e32 v12, vcc, s79, v12
	s_nop 1
	v_addc_co_u32_e32 v13, vcc, 0, v13, vcc
	global_load_dword v86, v[12:13], off
	v_add_co_u32_e32 v12, vcc, s79, v12
	s_nop 1
	v_addc_co_u32_e32 v13, vcc, 0, v13, vcc
	global_load_dword v88, v[12:13], off
	v_add_co_u32_e32 v12, vcc, s79, v12
	s_nop 1
	v_addc_co_u32_e32 v13, vcc, 0, v13, vcc
	global_load_dword v90, v[12:13], off
	v_add_co_u32_e32 v12, vcc, s79, v12
	s_nop 1
	v_addc_co_u32_e32 v13, vcc, 0, v13, vcc
	global_load_dword v92, v[12:13], off
	v_add_co_u32_e32 v12, vcc, s79, v12
	s_nop 1
	v_addc_co_u32_e32 v13, vcc, 0, v13, vcc
	global_load_dword v94, v[12:13], off
	v_add_co_u32_e32 v12, vcc, s79, v12
	s_nop 1
	v_addc_co_u32_e32 v13, vcc, 0, v13, vcc
	global_load_dword v96, v[12:13], off
	v_add_co_u32_e32 v12, vcc, s79, v12
	s_nop 1
	v_addc_co_u32_e32 v13, vcc, 0, v13, vcc
	global_load_dword v98, v[12:13], off
	v_add_co_u32_e32 v12, vcc, s79, v12
	s_nop 1
	v_addc_co_u32_e32 v13, vcc, 0, v13, vcc
	global_load_dword v100, v[12:13], off
	v_add_co_u32_e32 v12, vcc, s79, v12
	s_nop 1
	v_addc_co_u32_e32 v13, vcc, 0, v13, vcc
	global_load_dword v102, v[12:13], off
	v_add_co_u32_e32 v12, vcc, s79, v12
	s_nop 1
	v_addc_co_u32_e32 v13, vcc, 0, v13, vcc
	global_load_dword v104, v[12:13], off
	v_add_co_u32_e32 v12, vcc, s79, v12
	s_nop 1
	v_addc_co_u32_e32 v13, vcc, 0, v13, vcc
	global_load_dword v106, v[12:13], off
	v_add_co_u32_e32 v12, vcc, s79, v12
	s_nop 1
	v_addc_co_u32_e32 v13, vcc, 0, v13, vcc
	global_load_dword v108, v[12:13], off
	v_add_co_u32_e32 v12, vcc, s79, v12
	s_nop 1
	v_addc_co_u32_e32 v13, vcc, 0, v13, vcc
	global_load_dword v110, v[12:13], off
	v_add_co_u32_e32 v12, vcc, s79, v12
	s_nop 1
	v_addc_co_u32_e32 v13, vcc, 0, v13, vcc
	global_load_dword v112, v[12:13], off
	v_add_co_u32_e32 v12, vcc, s79, v12
	s_nop 1
	v_addc_co_u32_e32 v13, vcc, 0, v13, vcc
	global_load_dword v114, v[12:13], off
	v_add_co_u32_e32 v12, vcc, s79, v12
	s_nop 1
	v_addc_co_u32_e32 v13, vcc, 0, v13, vcc
	global_load_dword v116, v[12:13], off
	v_add_co_u32_e32 v12, vcc, s79, v12
	s_nop 1
	v_addc_co_u32_e32 v13, vcc, 0, v13, vcc
	global_load_dword v118, v[12:13], off
	v_add_co_u32_e32 v12, vcc, s79, v12
	s_nop 1
	v_addc_co_u32_e32 v13, vcc, 0, v13, vcc
	global_load_dword v120, v[12:13], off
	v_add_co_u32_e32 v12, vcc, s79, v12
	s_nop 1
	v_addc_co_u32_e32 v13, vcc, 0, v13, vcc
	global_load_dword v122, v[12:13], off
	s_add_u32 s8, s8, 0x60000
	s_addc_u32 s9, s9, 0
	s_waitcnt vmcnt(0)
	ds_read_b128 v[12:15], v9
	ds_read_b128 v[16:19], v9 offset:4096
	ds_read_b128 v[20:23], v9 offset:8192
	ds_read_b128 v[24:27], v9 offset:12288
	ds_read_b128 v[28:31], v9 offset:16384
	s_waitcnt lgkmcnt(4)
	v_mov_b32_e32 v40, v12
	s_waitcnt lgkmcnt(3)
	v_mov_b32_e32 v41, v16
	s_waitcnt lgkmcnt(2)
	v_mov_b32_e32 v42, v20
	s_waitcnt lgkmcnt(1)
	v_mov_b32_e32 v43, v24
	v_mov_b32_e32 v16, v13
	v_mov_b32_e32 v24, v21
	v_mov_b32_e32 v12, v14
	v_mov_b32_e32 v13, v18
	v_mov_b32_e32 v20, v22
	v_mov_b32_e32 v21, v26
	v_mov_b32_e32 v18, v15
	v_mov_b32_e32 v26, v23
	v_add_u32_e32 v9, 16, v9
	v_pk_fma_f32 v[4:5], v[60:61], v[40:41], v[4:5] op_sel_hi:[0,1,1]
	v_pk_fma_f32 v[6:7], v[60:61], v[42:43], v[6:7] op_sel_hi:[0,1,1]
	s_waitcnt lgkmcnt(0)
	v_fmac_f32_e32 v10, v60, v28
	v_pk_fma_f32 v[4:5], v[62:63], v[16:17], v[4:5] op_sel_hi:[0,1,1]
	v_pk_fma_f32 v[6:7], v[62:63], v[24:25], v[6:7] op_sel_hi:[0,1,1]
	v_fmac_f32_e32 v10, v62, v29
	v_pk_fma_f32 v[4:5], v[64:65], v[12:13], v[4:5] op_sel_hi:[0,1,1]
	v_pk_fma_f32 v[6:7], v[64:65], v[20:21], v[6:7] op_sel_hi:[0,1,1]
	v_fmac_f32_e32 v10, v64, v30
	v_pk_fma_f32 v[4:5], v[66:67], v[18:19], v[4:5] op_sel_hi:[0,1,1]
	v_pk_fma_f32 v[6:7], v[66:67], v[26:27], v[6:7] op_sel_hi:[0,1,1]
	v_fmac_f32_e32 v10, v66, v31
	ds_read_b128 v[12:15], v9
	ds_read_b128 v[16:19], v9 offset:4096
	ds_read_b128 v[20:23], v9 offset:8192
	ds_read_b128 v[24:27], v9 offset:12288
	ds_read_b128 v[28:31], v9 offset:16384
	s_waitcnt lgkmcnt(4)
	v_mov_b32_e32 v40, v12
	s_waitcnt lgkmcnt(3)
	v_mov_b32_e32 v41, v16
	s_waitcnt lgkmcnt(2)
	v_mov_b32_e32 v42, v20
	s_waitcnt lgkmcnt(1)
; DEV void phase_prologue(const Params& p, char* smem) {
;     ...
;       const int cc = tid & 63, kg = tid >> 6;
;       float a[5] = {0, 0, 0, 0, 0};
;       const float* wp = p.w_ada + (size_t)l * 1024 * 3072 + n0 + cc;
; #pragma unroll 4
;       for (int k = kg * 128; k < kg * 128 + 128; ++k) {
;         const float w = wp[(size_t)k * 3072];
; #pragma unroll
;         for (int rr = 0; rr < 5; ++rr) a[rr] += sv[rr * 1024 + k] * w;
;       }
	v_mov_b32_e32 v43, v24
	v_mov_b32_e32 v16, v13
	v_mov_b32_e32 v24, v21
	v_mov_b32_e32 v12, v14
	v_mov_b32_e32 v13, v18
	v_mov_b32_e32 v20, v22
	v_mov_b32_e32 v21, v26
	v_mov_b32_e32 v18, v15
	v_mov_b32_e32 v26, v23
	v_add_u32_e32 v9, 16, v9
	v_pk_fma_f32 v[4:5], v[68:69], v[40:41], v[4:5] op_sel_hi:[0,1,1]
	v_pk_fma_f32 v[6:7], v[68:69], v[42:43], v[6:7] op_sel_hi:[0,1,1]
	s_waitcnt lgkmcnt(0)
	v_fmac_f32_e32 v10, v68, v28
	v_pk_fma_f32 v[4:5], v[70:71], v[16:17], v[4:5] op_sel_hi:[0,1,1]
	v_pk_fma_f32 v[6:7], v[70:71], v[24:25], v[6:7] op_sel_hi:[0,1,1]
	v_fmac_f32_e32 v10, v70, v29
	v_pk_fma_f32 v[4:5], v[72:73], v[12:13], v[4:5] op_sel_hi:[0,1,1]
	v_pk_fma_f32 v[6:7], v[72:73], v[20:21], v[6:7] op_sel_hi:[0,1,1]
	v_fmac_f32_e32 v10, v72, v30
	v_pk_fma_f32 v[4:5], v[74:75], v[18:19], v[4:5] op_sel_hi:[0,1,1]
	v_pk_fma_f32 v[6:7], v[74:75], v[26:27], v[6:7] op_sel_hi:[0,1,1]
	v_fmac_f32_e32 v10, v74, v31
	ds_read_b128 v[12:15], v9
	ds_read_b128 v[16:19], v9 offset:4096
	ds_read_b128 v[20:23], v9 offset:8192
	ds_read_b128 v[24:27], v9 offset:12288
	ds_read_b128 v[28:31], v9 offset:16384
	s_waitcnt lgkmcnt(4)
	v_mov_b32_e32 v40, v12
	s_waitcnt lgkmcnt(3)
	v_mov_b32_e32 v41, v16
	s_waitcnt lgkmcnt(2)
	v_mov_b32_e32 v42, v20
	s_waitcnt lgkmcnt(1)
	v_mov_b32_e32 v43, v24
	v_mov_b32_e32 v16, v13
	v_mov_b32_e32 v24, v21
	v_mov_b32_e32 v12, v14
	v_mov_b32_e32 v13, v18
	v_mov_b32_e32 v20, v22
	v_mov_b32_e32 v21, v26
	v_mov_b32_e32 v18, v15
	v_mov_b32_e32 v26, v23
	v_add_u32_e32 v9, 16, v9
	v_pk_fma_f32 v[4:5], v[76:77], v[40:41], v[4:5] op_sel_hi:[0,1,1]
	v_pk_fma_f32 v[6:7], v[76:77], v[42:43], v[6:7] op_sel_hi:[0,1,1]
	s_waitcnt lgkmcnt(0)
	v_fmac_f32_e32 v10, v76, v28
	v_pk_fma_f32 v[4:5], v[78:79], v[16:17], v[4:5] op_sel_hi:[0,1,1]
	v_pk_fma_f32 v[6:7], v[78:79], v[24:25], v[6:7] op_sel_hi:[0,1,1]
	v_fmac_f32_e32 v10, v78, v29
	v_pk_fma_f32 v[4:5], v[80:81], v[12:13], v[4:5] op_sel_hi:[0,1,1]
	v_pk_fma_f32 v[6:7], v[80:81], v[20:21], v[6:7] op_sel_hi:[0,1,1]
	v_fmac_f32_e32 v10, v80, v30
	v_pk_fma_f32 v[4:5], v[82:83], v[18:19], v[4:5] op_sel_hi:[0,1,1]
	v_pk_fma_f32 v[6:7], v[82:83], v[26:27], v[6:7] op_sel_hi:[0,1,1]
	v_fmac_f32_e32 v10, v82, v31
	ds_read_b128 v[12:15], v9
	ds_read_b128 v[16:19], v9 offset:4096
	ds_read_b128 v[20:23], v9 offset:8192
	ds_read_b128 v[24:27], v9 offset:12288
	ds_read_b128 v[28:31], v9 offset:16384
	s_waitcnt lgkmcnt(4)
	v_mov_b32_e32 v40, v12
	s_waitcnt lgkmcnt(3)
	v_mov_b32_e32 v41, v16
	s_waitcnt lgkmcnt(2)
	v_mov_b32_e32 v42, v20
	s_waitcnt lgkmcnt(1)
	v_mov_b32_e32 v43, v24
	v_mov_b32_e32 v16, v13
	v_mov_b32_e32 v24, v21
	v_mov_b32_e32 v12, v14
	v_mov_b32_e32 v13, v18
	v_mov_b32_e32 v20, v22
	v_mov_b32_e32 v21, v26
	v_mov_b32_e32 v18, v15
	v_mov_b32_e32 v26, v23
	v_add_u32_e32 v9, 16, v9
	v_pk_fma_f32 v[4:5], v[84:85], v[40:41], v[4:5] op_sel_hi:[0,1,1]
	v_pk_fma_f32 v[6:7], v[84:85], v[42:43], v[6:7] op_sel_hi:[0,1,1]
	s_waitcnt lgkmcnt(0)
	v_fmac_f32_e32 v10, v84, v28
	v_pk_fma_f32 v[4:5], v[86:87], v[16:17], v[4:5] op_sel_hi:[0,1,1]
	v_pk_fma_f32 v[6:7], v[86:87], v[24:25], v[6:7] op_sel_hi:[0,1,1]
	v_fmac_f32_e32 v10, v86, v29
	v_pk_fma_f32 v[4:5], v[88:89], v[12:13], v[4:5] op_sel_hi:[0,1,1]
	v_pk_fma_f32 v[6:7], v[88:89], v[20:21], v[6:7] op_sel_hi:[0,1,1]
	v_fmac_f32_e32 v10, v88, v30
	v_pk_fma_f32 v[4:5], v[90:91], v[18:19], v[4:5] op_sel_hi:[0,1,1]
	v_pk_fma_f32 v[6:7], v[90:91], v[26:27], v[6:7] op_sel_hi:[0,1,1]
	v_fmac_f32_e32 v10, v90, v31
	ds_read_b128 v[12:15], v9
	ds_read_b128 v[16:19], v9 offset:4096
	ds_read_b128 v[20:23], v9 offset:8192
	ds_read_b128 v[24:27], v9 offset:12288
	ds_read_b128 v[28:31], v9 offset:16384
	s_waitcnt lgkmcnt(4)
	v_mov_b32_e32 v40, v12
	s_waitcnt lgkmcnt(3)
	v_mov_b32_e32 v41, v16
	s_waitcnt lgkmcnt(2)
	v_mov_b32_e32 v42, v20
	s_waitcnt lgkmcnt(1)
	v_mov_b32_e32 v43, v24
	v_mov_b32_e32 v16, v13
	v_mov_b32_e32 v24, v21
	v_mov_b32_e32 v12, v14
	v_mov_b32_e32 v13, v18
	v_mov_b32_e32 v20, v22
	v_mov_b32_e32 v21, v26
	v_mov_b32_e32 v18, v15
	v_mov_b32_e32 v26, v23
	v_add_u32_e32 v9, 16, v9
	v_pk_fma_f32 v[4:5], v[92:93], v[40:41], v[4:5] op_sel_hi:[0,1,1]
	v_pk_fma_f32 v[6:7], v[92:93], v[42:43], v[6:7] op_sel_hi:[0,1,1]
	s_waitcnt lgkmcnt(0)
	v_fmac_f32_e32 v10, v92, v28
	v_pk_fma_f32 v[4:5], v[94:95], v[16:17], v[4:5] op_sel_hi:[0,1,1]
	v_pk_fma_f32 v[6:7], v[94:95], v[24:25], v[6:7] op_sel_hi:[0,1,1]
	v_fmac_f32_e32 v10, v94, v29
	v_pk_fma_f32 v[4:5], v[96:97], v[12:13], v[4:5] op_sel_hi:[0,1,1]
	v_pk_fma_f32 v[6:7], v[96:97], v[20:21], v[6:7] op_sel_hi:[0,1,1]
	v_fmac_f32_e32 v10, v96, v30
	v_pk_fma_f32 v[4:5], v[98:99], v[18:19], v[4:5] op_sel_hi:[0,1,1]
	v_pk_fma_f32 v[6:7], v[98:99], v[26:27], v[6:7] op_sel_hi:[0,1,1]
	v_fmac_f32_e32 v10, v98, v31
	ds_read_b128 v[12:15], v9
	ds_read_b128 v[16:19], v9 offset:4096
	ds_read_b128 v[20:23], v9 offset:8192
	ds_read_b128 v[24:27], v9 offset:12288
	ds_read_b128 v[28:31], v9 offset:16384
	s_waitcnt lgkmcnt(4)
	v_mov_b32_e32 v40, v12
	s_waitcnt lgkmcnt(3)
	v_mov_b32_e32 v41, v16
	s_waitcnt lgkmcnt(2)
	v_mov_b32_e32 v42, v20
	s_waitcnt lgkmcnt(1)
	v_mov_b32_e32 v43, v24
	v_mov_b32_e32 v16, v13
	v_mov_b32_e32 v24, v21
	v_mov_b32_e32 v12, v14
	v_mov_b32_e32 v13, v18
	v_mov_b32_e32 v20, v22
	v_mov_b32_e32 v21, v26
	v_mov_b32_e32 v18, v15
	v_mov_b32_e32 v26, v23
	v_add_u32_e32 v9, 16, v9
	v_pk_fma_f32 v[4:5], v[100:101], v[40:41], v[4:5] op_sel_hi:[0,1,1]
	v_pk_fma_f32 v[6:7], v[100:101], v[42:43], v[6:7] op_sel_hi:[0,1,1]
	s_waitcnt lgkmcnt(0)
; DEV void phase_prologue(const Params& p, char* smem) {
;     ...
;       for (int k = kg * 128; k < kg * 128 + 128; ++k) {
;         const float w = wp[(size_t)k * 3072];
; #pragma unroll
;         for (int rr = 0; rr < 5; ++rr) a[rr] += sv[rr * 1024 + k] * w;
;       }
; #pragma unroll
;       for (int rr = 0; rr < 5; ++rr) red[(kg * 5 + rr) * 64 + cc] = a[rr];
;       __syncthreads();
;       if (tid < 320) {
;         const int rr = tid >> 6, c2 = tid & 63;
;         float s = 0;
; #pragma unroll
;         for (int g = 0; g < 8; ++g) s += red[(g * 5 + rr) * 64 + c2];
;         s += p.b_ada[l * 3072 + n0 + c2];
;         ((float*)(ws + OFF_MOD))[(l * 5 + rr) * 3072 + n0 + c2] = s;
	v_fmac_f32_e32 v10, v100, v28
	v_pk_fma_f32 v[4:5], v[102:103], v[16:17], v[4:5] op_sel_hi:[0,1,1]
	v_pk_fma_f32 v[6:7], v[102:103], v[24:25], v[6:7] op_sel_hi:[0,1,1]
	v_fmac_f32_e32 v10, v102, v29
	v_pk_fma_f32 v[4:5], v[104:105], v[12:13], v[4:5] op_sel_hi:[0,1,1]
	v_pk_fma_f32 v[6:7], v[104:105], v[20:21], v[6:7] op_sel_hi:[0,1,1]
	v_fmac_f32_e32 v10, v104, v30
	v_pk_fma_f32 v[4:5], v[106:107], v[18:19], v[4:5] op_sel_hi:[0,1,1]
	v_pk_fma_f32 v[6:7], v[106:107], v[26:27], v[6:7] op_sel_hi:[0,1,1]
	v_fmac_f32_e32 v10, v106, v31
	ds_read_b128 v[12:15], v9
	ds_read_b128 v[16:19], v9 offset:4096
	ds_read_b128 v[20:23], v9 offset:8192
	ds_read_b128 v[24:27], v9 offset:12288
	ds_read_b128 v[28:31], v9 offset:16384
	s_waitcnt lgkmcnt(4)
	v_mov_b32_e32 v40, v12
	s_waitcnt lgkmcnt(3)
	v_mov_b32_e32 v41, v16
	s_waitcnt lgkmcnt(2)
	v_mov_b32_e32 v42, v20
	s_waitcnt lgkmcnt(1)
	v_mov_b32_e32 v43, v24
	v_mov_b32_e32 v16, v13
	v_mov_b32_e32 v24, v21
	v_mov_b32_e32 v12, v14
	v_mov_b32_e32 v13, v18
	v_mov_b32_e32 v20, v22
	v_mov_b32_e32 v21, v26
	v_mov_b32_e32 v18, v15
	v_mov_b32_e32 v26, v23
	v_add_u32_e32 v9, 16, v9
	v_pk_fma_f32 v[4:5], v[108:109], v[40:41], v[4:5] op_sel_hi:[0,1,1]
	v_pk_fma_f32 v[6:7], v[108:109], v[42:43], v[6:7] op_sel_hi:[0,1,1]
	s_waitcnt lgkmcnt(0)
	v_fmac_f32_e32 v10, v108, v28
	v_pk_fma_f32 v[4:5], v[110:111], v[16:17], v[4:5] op_sel_hi:[0,1,1]
	v_pk_fma_f32 v[6:7], v[110:111], v[24:25], v[6:7] op_sel_hi:[0,1,1]
	v_fmac_f32_e32 v10, v110, v29
	v_pk_fma_f32 v[4:5], v[112:113], v[12:13], v[4:5] op_sel_hi:[0,1,1]
	v_pk_fma_f32 v[6:7], v[112:113], v[20:21], v[6:7] op_sel_hi:[0,1,1]
	v_fmac_f32_e32 v10, v112, v30
	v_pk_fma_f32 v[4:5], v[114:115], v[18:19], v[4:5] op_sel_hi:[0,1,1]
	v_pk_fma_f32 v[6:7], v[114:115], v[26:27], v[6:7] op_sel_hi:[0,1,1]
	v_fmac_f32_e32 v10, v114, v31
	ds_read_b128 v[12:15], v9
	ds_read_b128 v[16:19], v9 offset:4096
	ds_read_b128 v[20:23], v9 offset:8192
	ds_read_b128 v[24:27], v9 offset:12288
	ds_read_b128 v[28:31], v9 offset:16384
	s_waitcnt lgkmcnt(4)
	v_mov_b32_e32 v40, v12
	s_waitcnt lgkmcnt(3)
	v_mov_b32_e32 v41, v16
	s_waitcnt lgkmcnt(2)
	v_mov_b32_e32 v42, v20
	s_waitcnt lgkmcnt(1)
	v_mov_b32_e32 v43, v24
	v_mov_b32_e32 v16, v13
	v_mov_b32_e32 v24, v21
	v_mov_b32_e32 v12, v14
	v_mov_b32_e32 v13, v18
	v_mov_b32_e32 v20, v22
	v_mov_b32_e32 v21, v26
	v_mov_b32_e32 v18, v15
	v_mov_b32_e32 v26, v23
	v_add_u32_e32 v9, 16, v9
	v_pk_fma_f32 v[4:5], v[116:117], v[40:41], v[4:5] op_sel_hi:[0,1,1]
	v_pk_fma_f32 v[6:7], v[116:117], v[42:43], v[6:7] op_sel_hi:[0,1,1]
	s_waitcnt lgkmcnt(0)
	v_fmac_f32_e32 v10, v116, v28
	v_pk_fma_f32 v[4:5], v[118:119], v[16:17], v[4:5] op_sel_hi:[0,1,1]
	v_pk_fma_f32 v[6:7], v[118:119], v[24:25], v[6:7] op_sel_hi:[0,1,1]
	v_fmac_f32_e32 v10, v118, v29
	v_pk_fma_f32 v[4:5], v[120:121], v[12:13], v[4:5] op_sel_hi:[0,1,1]
	v_pk_fma_f32 v[6:7], v[120:121], v[20:21], v[6:7] op_sel_hi:[0,1,1]
	v_fmac_f32_e32 v10, v120, v30
	v_pk_fma_f32 v[4:5], v[122:123], v[18:19], v[4:5] op_sel_hi:[0,1,1]
	v_pk_fma_f32 v[6:7], v[122:123], v[26:27], v[6:7] op_sel_hi:[0,1,1]
	v_fmac_f32_e32 v10, v122, v31
	s_cmp_eq_u32 s8, 0x180000
	s_cbranch_scc0 .LBB0_515
	v_lshl_add_u32 v2, v1, 2, 0
	s_movk_i32 s8, 0x500
	v_mad_u64_u32 v[12:13], s[8:9], v8, s8, v[2:3]
	s_movk_i32 s8, 0x140
	s_nop 0
	v_cmp_gt_i32_e32 vcc, s8, v0
	ds_write2st64_b32 v12, v4, v5 offset0:80 offset1:81
	ds_write2st64_b32 v12, v6, v7 offset0:82 offset1:83
	ds_write_b32 v12, v10 offset:21504
	s_waitcnt lgkmcnt(0)
	s_barrier
	s_and_saveexec_b64 s[8:9], vcc
	s_cbranch_execz .LBB0_518
	s_and_b64 s[20:21], s[6:7], exec
	s_cselect_b32 s19, 0xc00, 0
	v_readlane_b32 s20, v240, 7
	s_add_i32 s19, s20, s19
	v_readlane_b32 s52, v241, 51
	v_or_b32_e32 v144, s19, v1
	v_readlane_b32 s64, v241, 63
	v_readlane_b32 s65, v240, 0
	v_lshl_add_u32 v0, v8, 8, v2
	s_and_b64 s[6:7], s[6:7], exec
	v_lshl_add_u64 v[4:5], v[144:145], 2, s[64:65]
	global_load_dword v9, v[4:5], off
	ds_read2st64_b32 v[2:3], v0 offset0:80 offset1:85
	ds_read2st64_b32 v[4:5], v0 offset0:90 offset1:95
	ds_read2st64_b32 v[6:7], v0 offset0:100 offset1:105
	ds_read2st64_b32 v[10:11], v0 offset0:110 offset1:115
	s_cselect_b32 s6, 5, 0
	s_waitcnt lgkmcnt(3)
	v_add_f32_e32 v2, 0, v2
	v_add_f32_e32 v2, v2, v3
	s_waitcnt lgkmcnt(2)
	v_add_f32_e32 v2, v2, v4
	v_add_u32_e32 v0, s6, v8
	v_add_f32_e32 v2, v2, v5
	v_mul_lo_u32 v0, v0, s80
	s_waitcnt lgkmcnt(1)
	v_add_f32_e32 v2, v2, v6
	v_add_u32_e32 v0, s20, v0
	v_add_f32_e32 v2, v2, v7
	v_or_b32_e32 v0, v0, v1
	s_waitcnt lgkmcnt(0)
	v_add_f32_e32 v2, v2, v10
	v_ashrrev_i32_e32 v1, 31, v0
	v_add_f32_e32 v2, v2, v11
	v_lshl_add_u64 v[0:1], v[0:1], 2, s[2:3]
	v_readlane_b32 s21, v240, 8
	v_readlane_b32 s53, v241, 52
	v_readlane_b32 s54, v241, 53
	v_readlane_b32 s55, v241, 54
	v_readlane_b32 s56, v241, 55
	v_readlane_b32 s57, v241, 56
	v_readlane_b32 s58, v241, 57
	v_readlane_b32 s59, v241, 58
	v_readlane_b32 s60, v241, 59
	v_readlane_b32 s61, v241, 60
	v_readlane_b32 s62, v241, 61
	v_readlane_b32 s63, v241, 62
	v_readlane_b32 s66, v240, 1
	v_readlane_b32 s67, v240, 2
	s_waitcnt vmcnt(0)
	v_add_f32_e32 v2, v2, v9
	flat_store_dword v[0:1], v2
